# SGU: per-head W_s and u loads issued before the next-head v-tile loads so the MFMA section's counted waits no longer block on the HBM v-tile loads; waits re-derived
# speedup vs baseline: 1.0010x; 1.0009x over previous
; __device__ __forceinline__ unsigned cvt_pk_bf16(float lo, float hi) { unsigned r; asm volatile("v_cvt_pk_bf16_f32 %0, %1, %2" : "=v"(r) : "v"(lo), "v"(hi)); return r; }
; __device__ __forceinline__ void sgu_phase(const Ctx& C, const bf16_t* Z1, const float* VSS, const float* gv, const bf16_t* WSB, const float* bs, bf16_t* Gout) {
;     ...
;                 const f32x4 ga = *(const f32x4*)(gv + 128 * h + 8 * ch), gb = *(const f32x4*)(gv + 128 * h + 8 * ch + 4);
;     ...
;             for (int mt = 0; mt < 2; ++mt) { const int t = 32 * tb + 16 * mt + fr; const float bias = bs[h * 128 + t];
; #pragma unroll
;                 for (int nt = 0; nt < 4; ++nt) { const int d = 128 * h + 64 * dh + 16 * nt + 4 * g4; const u32x2 u2 = uu[mt][nt];
;                     u32x2 o; o.x = cvt_pk_bf16(bflo(u2.x) * (acc[mt][nt][0] + bias), bfhi(u2.x) * (acc[mt][nt][1] + bias)); o.y = cvt_pk_bf16(bflo(u2.y) * (acc[mt][nt][2] + bias), bfhi(u2.y) * (acc[mt][nt][3] + bias));
;                     *(u32x2*)(Gout + (size_t)(tok0 + t) * DM + d) = o; } }
;             __syncthreads();
.LBB0_219:
	s_waitcnt vmcnt(13)
	v_lshl_add_u64 v[48:49], v[90:91], 0, s[0:1]
	s_waitcnt vmcnt(12)
	flat_load_dword v52, v[48:49]
	flat_load_dword v70, v[48:49] offset:64
	v_lshl_add_u64 v[50:51], v[80:81], 0, s[0:1]
	global_load_dwordx4 v[72:75], v[50:51], off offset:512
	global_load_dwordx4 v[76:79], v[50:51], off offset:528
	v_lshl_add_u64 v[50:51], s[66:67], 0, v[152:153]
	s_mov_b32 s22, 0x30800000
	s_waitcnt vmcnt(0)
	v_lshlrev_b32_e32 v53, 16, v180
	v_and_b32_e32 v54, 0xffff0000, v180
	v_lshlrev_b32_e32 v55, 16, v181
	v_and_b32_e32 v56, 0xffff0000, v181
	v_lshlrev_b32_e32 v66, 16, v174
	v_and_b32_e32 v67, 0xffff0000, v174
	v_add_co_u32_e32 v50, vcc, s22, v50
	v_lshlrev_b32_e32 v57, 16, v178
	v_and_b32_e32 v58, 0xffff0000, v178
	v_lshlrev_b32_e32 v59, 16, v179
	v_and_b32_e32 v60, 0xffff0000, v179
	v_addc_co_u32_e32 v51, vcc, 0, v51, vcc
	v_lshlrev_b32_e32 v61, 16, v176
	v_and_b32_e32 v62, 0xffff0000, v176
	v_lshlrev_b32_e32 v63, 16, v177
	v_and_b32_e32 v64, 0xffff0000, v177
	v_lshlrev_b32_e32 v68, 16, v175
	v_and_b32_e32 v69, 0xffff0000, v175
	s_mov_b64 vcc, 0x8000
	v_lshl_add_u64 v[164:165], v[164:165], 0, vcc
	v_lshl_add_u64 v[162:163], v[162:163], 0, vcc
	v_lshl_add_u64 v[160:161], v[160:161], 0, vcc
	v_lshl_add_u64 v[158:159], v[158:159], 0, vcc
	s_add_u32 s0, s0, 0x200
	s_mov_b64 s[80:81], 0x100
	s_addc_u32 s1, s1, 0
	v_lshl_add_u64 v[142:143], v[142:143], 0, s[80:81]
	v_lshl_add_u64 v[144:145], v[144:145], 0, s[80:81]
	v_lshl_add_u64 v[146:147], v[146:147], 0, s[80:81]
	v_lshl_add_u64 v[148:149], v[148:149], 0, s[80:81]
	v_lshl_add_u64 v[152:153], v[152:153], 0, s[80:81]
	v_lshl_add_u64 v[154:155], v[154:155], 0, s[80:81]
	s_cmpk_eq_i32 s0, 0x1e00
	v_lshl_add_u64 v[156:157], v[156:157], 0, s[80:81]
	s_waitcnt lgkmcnt(0)
	v_add_f32_e32 v44, v52, v44
	v_add_f32_e32 v45, v52, v45
	v_add_f32_e32 v46, v52, v46
	v_add_f32_e32 v47, v52, v47
	v_add_f32_e32 v32, v32, v52
	v_add_f32_e32 v33, v33, v52
	v_add_f32_e32 v40, v40, v52
	v_add_f32_e32 v41, v41, v52
	v_add_f32_e32 v42, v42, v52
	v_add_f32_e32 v43, v43, v52
	v_add_f32_e32 v36, v36, v52
	v_add_f32_e32 v37, v37, v52
	v_add_f32_e32 v38, v38, v52
	v_add_f32_e32 v39, v39, v52
	v_add_f32_e32 v34, v34, v52
	v_add_f32_e32 v35, v35, v52
	v_mul_f32_e32 v44, v44, v53
	v_mul_f32_e32 v45, v45, v54
	v_mul_f32_e32 v46, v46, v55
	v_mul_f32_e32 v47, v47, v56
	v_mul_f32_e32 v52, v32, v66
	v_mul_f32_e32 v53, v33, v67
	v_cvt_pk_bf16_f32 v32, v44, v45
	v_cvt_pk_bf16_f32 v33, v46, v47
	v_mul_f32_e32 v40, v40, v57
	v_mul_f32_e32 v41, v41, v58
	v_mul_f32_e32 v42, v42, v59
	v_mul_f32_e32 v43, v43, v60
	global_store_dwordx2 v[50:51], v[32:33], off
	v_cvt_pk_bf16_f32 v32, v40, v41
	v_cvt_pk_bf16_f32 v33, v42, v43
	v_mul_f32_e32 v36, v36, v61
	v_mul_f32_e32 v37, v37, v62
	v_mul_f32_e32 v38, v38, v63
	v_mul_f32_e32 v39, v39, v64
	global_store_dwordx2 v[50:51], v[32:33], off offset:32
	v_cvt_pk_bf16_f32 v32, v36, v37
	v_cvt_pk_bf16_f32 v33, v38, v39
	v_mul_f32_e32 v34, v34, v68
	v_mul_f32_e32 v35, v35, v69
	global_store_dwordx2 v[50:51], v[32:33], off offset:64
	v_cvt_pk_bf16_f32 v32, v52, v53
	v_cvt_pk_bf16_f32 v33, v34, v35
	global_store_dwordx2 v[50:51], v[32:33], off offset:96
	v_lshl_add_u64 v[32:33], s[66:67], 0, v[150:151]
	v_lshlrev_b32_e32 v35, 16, v172
	v_and_b32_e32 v36, 0xffff0000, v172
	v_lshlrev_b32_e32 v37, 16, v173
	v_and_b32_e32 v38, 0xffff0000, v173
	v_lshlrev_b32_e32 v47, 16, v166
	v_and_b32_e32 v48, 0xffff0000, v166
	v_add_co_u32_e32 v32, vcc, s22, v32
	v_lshlrev_b32_e32 v39, 16, v170
	v_and_b32_e32 v40, 0xffff0000, v170
	v_lshlrev_b32_e32 v41, 16, v171
	v_and_b32_e32 v42, 0xffff0000, v171
	v_addc_co_u32_e32 v33, vcc, 0, v33, vcc
	v_lshlrev_b32_e32 v43, 16, v168
	v_and_b32_e32 v44, 0xffff0000, v168
	v_lshlrev_b32_e32 v45, 16, v169
	v_and_b32_e32 v46, 0xffff0000, v169
	v_lshlrev_b32_e32 v49, 16, v167
	v_and_b32_e32 v50, 0xffff0000, v167
	v_lshl_add_u64 v[150:151], v[150:151], 0, s[80:81]
	v_add_f32_e32 v28, v28, v70
	v_add_f32_e32 v29, v29, v70
	v_add_f32_e32 v30, v30, v70
	v_add_f32_e32 v31, v31, v70
	v_add_f32_e32 v16, v16, v70
	v_add_f32_e32 v17, v17, v70
	v_add_f32_e32 v24, v24, v70
	v_add_f32_e32 v25, v25, v70
	v_add_f32_e32 v26, v26, v70
	v_add_f32_e32 v27, v27, v70
	v_add_f32_e32 v20, v20, v70
	v_add_f32_e32 v21, v21, v70
	v_add_f32_e32 v22, v22, v70
	v_add_f32_e32 v23, v23, v70
	v_add_f32_e32 v18, v18, v70
	v_add_f32_e32 v19, v19, v70
	v_mul_f32_e32 v28, v28, v35
	v_mul_f32_e32 v29, v29, v36
	v_mul_f32_e32 v30, v30, v37
	v_mul_f32_e32 v31, v31, v38
	v_mul_f32_e32 v34, v16, v47
	v_mul_f32_e32 v35, v17, v48
	v_cvt_pk_bf16_f32 v16, v28, v29
	v_cvt_pk_bf16_f32 v17, v30, v31
	v_mul_f32_e32 v24, v24, v39
	v_mul_f32_e32 v25, v25, v40
	v_mul_f32_e32 v26, v26, v41
	v_mul_f32_e32 v27, v27, v42
	global_store_dwordx2 v[32:33], v[16:17], off
	v_cvt_pk_bf16_f32 v16, v24, v25
	v_cvt_pk_bf16_f32 v17, v26, v27
	v_mul_f32_e32 v20, v20, v43
	v_mul_f32_e32 v21, v21, v44
	v_mul_f32_e32 v22, v22, v45
	v_mul_f32_e32 v23, v23, v46
	global_store_dwordx2 v[32:33], v[16:17], off offset:32
	v_cvt_pk_bf16_f32 v16, v20, v21
	v_cvt_pk_bf16_f32 v17, v22, v23
	v_mul_f32_e32 v18, v18, v49
	v_mul_f32_e32 v19, v19, v50
	global_store_dwordx2 v[32:33], v[16:17], off offset:64
	v_cvt_pk_bf16_f32 v16, v34, v35
	v_cvt_pk_bf16_f32 v17, v18, v19
	global_store_dwordx2 v[32:33], v[16:17], off offset:96
	s_barrier
	s_cbranch_scc1 .LBB0_228
; #define LAS __attribute__((address_space(3)))
; __device__ __forceinline__ void sgu_phase(const Ctx& C, const bf16_t* Z1, const float* VSS, const float* gv, const bf16_t* WSB, const float* bs, bf16_t* Gout) {
;     ...
;                 for (int ps = 0; ps < 4; ++ps) { const int s = ps * 32 + srow; const u32x4 raw = vraw[ps]; const float r = rsv[s];
;                     u32x4 o; o.x = cvt_pk_bf16(bflo(raw.x) * r * ga[0], bfhi(raw.x) * r * ga[1]); o.y = cvt_pk_bf16(bflo(raw.y) * r * ga[2], bfhi(raw.y) * r * ga[3]);
;                     o.z = cvt_pk_bf16(bflo(raw.z) * r * gb[0], bfhi(raw.z) * r * gb[1]); o.w = cvt_pk_bf16(bflo(raw.w) * r * gb[2], bfhi(raw.w) * r * gb[3]);
;                     *(LAS u32x4*)(Vs + off_b(s, ch)) = o; }
;             }
;             if (h + 1 < 16) {
; #pragma unroll
;                 for (int ps = 0; ps < 4; ++ps) vraw[ps] = *(const u32x4*)(Z1 + (size_t)(tok0 + ps * 32 + srow) * 4096 + 2048 + 128 * (h + 1) + 8 * ch);
;             }
;             bf16x8 wf[4][2];
; #pragma unroll
;             for (int kk = 0; kk < 4; ++kk)
; #pragma unroll
;                 for (int mt = 0; mt < 2; ++mt) wf[kk][mt] = *(const bf16x8*)(WSB + ((size_t)h * 128 + 32 * tb + 16 * mt + fr) * 128 + 32 * (kk <= tb ? kk : tb) + 8 * g4);
;             u32x2 uu[2][4];
; #pragma unroll
;             for (int mt = 0; mt < 2; ++mt)
; #pragma unroll
;                 for (int nt = 0; nt < 4; ++nt) uu[mt][nt] = *(const u32x2*)(Z1 + (size_t)(tok0 + 32 * tb + 16 * mt + fr) * 4096 + 128 * h + 64 * dh + 16 * nt + 4 * g4);
;             __syncthreads();
;             f32x4 acc[2][4];
; #pragma unroll
;             for (int a = 0; a < 2; ++a)
; #pragma unroll
;                 for (int b = 0; b < 4; ++b) acc[a][b] = (f32x4){0.f, 0.f, 0.f, 0.f};
; #pragma unroll
;             for (int kk = 0; kk < 4; ++kk) {
;                 if (kk <= tb) {
;                     unsigned ad[8]; bf16x8 vf[4];
; #pragma unroll
;                     for (int nt = 0; nt < 4; ++nt) { ad[2 * nt] = ldsbase + tr_read_addr_16(lane, 4 * dh + nt, kk, 0); ad[2 * nt + 1] = ldsbase + tr_read_addr_16(lane, 4 * dh + nt, kk, 1); }
;                     tr_read8(vf, ad);
; #pragma unroll
;                     for (int nt = 0; nt < 4; ++nt)
; #pragma unroll
;                         for (int mt = 0; mt < 2; ++mt) acc[mt][nt] = __builtin_amdgcn_mfma_f32_16x16x32_bf16(vf[nt], wf[kk][mt], acc[mt][nt], 0, 0, 0);
.LBB0_220:
	v_mov_b64_e32 v[20:21], v[72:73]
	v_mov_b64_e32 v[22:23], v[74:75]
	v_mov_b64_e32 v[16:17], v[76:77]
	v_mov_b64_e32 v[18:19], v[78:79]
	ds_read_b32 v24, v183 offset:32768
	v_lshlrev_b32_e32 v25, 16, v12
	v_and_b32_e32 v12, 0xffff0000, v12
	v_add_u32_e32 v115, v182, v184
	s_mov_b32 s22, 0x1f01000
	s_waitcnt lgkmcnt(0)
	v_mul_f32_e32 v25, v24, v25
	v_mul_f32_e32 v12, v24, v12
	v_mul_f32_e32 v25, v20, v25
	v_mul_f32_e32 v12, v21, v12
	v_cvt_pk_bf16_f32 v12, v25, v12
	v_lshlrev_b32_e32 v25, 16, v13
	v_and_b32_e32 v13, 0xffff0000, v13
	v_mul_f32_e32 v25, v24, v25
	v_mul_f32_e32 v13, v24, v13
	v_mul_f32_e32 v25, v22, v25
	v_mul_f32_e32 v13, v23, v13
	v_cvt_pk_bf16_f32 v13, v25, v13
	v_lshlrev_b32_e32 v25, 16, v14
	v_and_b32_e32 v14, 0xffff0000, v14
	v_mul_f32_e32 v25, v24, v25
	v_mul_f32_e32 v14, v24, v14
	v_mul_f32_e32 v25, v16, v25
	v_mul_f32_e32 v14, v17, v14
	v_cvt_pk_bf16_f32 v14, v25, v14
	v_lshlrev_b32_e32 v25, 16, v15
	v_and_b32_e32 v15, 0xffff0000, v15
	v_mul_f32_e32 v15, v24, v15
	v_mul_f32_e32 v25, v24, v25
	v_mul_f32_e32 v15, v19, v15
	v_mul_f32_e32 v25, v18, v25
	v_cvt_pk_bf16_f32 v15, v25, v15
	ds_write_b128 v115, v[12:15]
	ds_read_b32 v12, v183 offset:32896
	v_lshlrev_b32_e32 v13, 16, v8
	v_and_b32_e32 v8, 0xffff0000, v8
	s_waitcnt lgkmcnt(0)
	v_mul_f32_e32 v13, v12, v13
	v_mul_f32_e32 v8, v12, v8
	v_mul_f32_e32 v13, v20, v13
	v_mul_f32_e32 v8, v21, v8
	v_cvt_pk_bf16_f32 v8, v13, v8
	v_lshlrev_b32_e32 v13, 16, v9
	v_and_b32_e32 v9, 0xffff0000, v9
	v_mul_f32_e32 v13, v12, v13
	v_mul_f32_e32 v9, v12, v9
	v_mul_f32_e32 v13, v22, v13
	v_mul_f32_e32 v9, v23, v9
	v_cvt_pk_bf16_f32 v9, v13, v9
	v_lshlrev_b32_e32 v13, 16, v10
	v_and_b32_e32 v10, 0xffff0000, v10
	v_mul_f32_e32 v13, v12, v13
	v_mul_f32_e32 v10, v12, v10
	v_mul_f32_e32 v13, v16, v13
	v_mul_f32_e32 v10, v17, v10
	v_cvt_pk_bf16_f32 v10, v13, v10
	v_lshlrev_b32_e32 v13, 16, v11
	v_and_b32_e32 v11, 0xffff0000, v11
	v_mul_f32_e32 v11, v12, v11
	v_mul_f32_e32 v13, v12, v13
	v_mul_f32_e32 v11, v19, v11
	v_mul_f32_e32 v13, v18, v13
	v_cvt_pk_bf16_f32 v11, v13, v11
	ds_write_b128 v230, v[8:11]
	ds_read_b32 v8, v183 offset:33024
	v_lshlrev_b32_e32 v9, 16, v4
	v_and_b32_e32 v4, 0xffff0000, v4
	s_waitcnt lgkmcnt(0)
	v_mul_f32_e32 v9, v8, v9
	v_mul_f32_e32 v4, v8, v4
	v_mul_f32_e32 v9, v20, v9
	v_mul_f32_e32 v4, v21, v4
	v_cvt_pk_bf16_f32 v4, v9, v4
	v_lshlrev_b32_e32 v9, 16, v5
	v_and_b32_e32 v5, 0xffff0000, v5
	v_mul_f32_e32 v9, v8, v9
	v_mul_f32_e32 v5, v8, v5
	v_mul_f32_e32 v9, v22, v9
	v_mul_f32_e32 v5, v23, v5
	v_cvt_pk_bf16_f32 v5, v9, v5
	v_lshlrev_b32_e32 v9, 16, v6
	v_and_b32_e32 v6, 0xffff0000, v6
	v_mul_f32_e32 v9, v8, v9
	v_mul_f32_e32 v6, v8, v6
	v_mul_f32_e32 v9, v16, v9
	v_mul_f32_e32 v6, v17, v6
	v_cvt_pk_bf16_f32 v6, v9, v6
	v_lshlrev_b32_e32 v9, 16, v7
	v_and_b32_e32 v7, 0xffff0000, v7
	v_mul_f32_e32 v7, v8, v7
	v_mul_f32_e32 v9, v8, v9
	v_mul_f32_e32 v7, v19, v7
	v_mul_f32_e32 v9, v18, v9
	v_cvt_pk_bf16_f32 v7, v9, v7
	ds_write_b128 v231, v[4:7]
	ds_read_b32 v4, v183 offset:33152
	v_lshlrev_b32_e32 v5, 16, v0
	v_and_b32_e32 v0, 0xffff0000, v0
	s_waitcnt lgkmcnt(0)
	v_mul_f32_e32 v5, v4, v5
	v_mul_f32_e32 v0, v4, v0
	v_mul_f32_e32 v5, v20, v5
	v_mul_f32_e32 v0, v21, v0
	v_cvt_pk_bf16_f32 v0, v5, v0
	v_lshlrev_b32_e32 v5, 16, v1
	v_and_b32_e32 v1, 0xffff0000, v1
	v_mul_f32_e32 v5, v4, v5
	v_mul_f32_e32 v1, v4, v1
	v_mul_f32_e32 v5, v22, v5
	v_mul_f32_e32 v1, v23, v1
	v_cvt_pk_bf16_f32 v1, v5, v1
	v_lshlrev_b32_e32 v5, 16, v2
	v_and_b32_e32 v2, 0xffff0000, v2
	v_mul_f32_e32 v5, v4, v5
	v_mul_f32_e32 v2, v4, v2
	v_mul_f32_e32 v5, v16, v5
	v_mul_f32_e32 v2, v17, v2
	v_cvt_pk_bf16_f32 v2, v5, v2
	v_lshlrev_b32_e32 v5, 16, v3
	v_and_b32_e32 v3, 0xffff0000, v3
	v_mul_f32_e32 v3, v4, v3
	v_mul_f32_e32 v5, v4, v5
	v_mul_f32_e32 v3, v19, v3
	v_mul_f32_e32 v5, v18, v5
	v_cvt_pk_bf16_f32 v3, v5, v3
	ds_write_b128 v232, v[0:3]
	v_lshl_add_u64 v[16:17], s[66:67], 0, v[158:159]
	v_add_co_u32_e32 v20, vcc, s22, v16
	s_nop 1
	v_addc_co_u32_e32 v21, vcc, 0, v17, vcc
	global_load_dwordx4 v[16:19], v[20:21], off offset:-4096
	global_load_dwordx4 v[76:79], v[20:21], off
	v_lshl_add_u64 v[20:21], s[66:67], 0, v[160:161]
	v_add_co_u32_e32 v20, vcc, s22, v20
	s_nop 1
	v_addc_co_u32_e32 v21, vcc, 0, v21, vcc
	global_load_dwordx4 v[68:71], v[20:21], off offset:-4096
	global_load_dwordx4 v[72:75], v[20:21], off
	v_lshl_add_u64 v[20:21], s[66:67], 0, v[162:163]
	v_add_co_u32_e32 v20, vcc, s22, v20
	s_nop 1
	v_addc_co_u32_e32 v21, vcc, 0, v21, vcc
	global_load_dwordx4 v[56:59], v[20:21], off offset:-4096
	global_load_dwordx4 v[60:63], v[20:21], off
	v_lshl_add_u64 v[20:21], s[66:67], 0, v[164:165]
	v_add_co_u32_e32 v20, vcc, s22, v20
	s_nop 1
	v_addc_co_u32_e32 v21, vcc, 0, v21, vcc
	global_load_dwordx4 v[48:51], v[20:21], off offset:-4096
	global_load_dwordx4 v[52:55], v[20:21], off
	v_lshl_add_u64 v[20:21], s[66:67], 0, v[154:155]
	global_load_dwordx2 v[180:181], v[20:21], off offset:-64
	global_load_dwordx2 v[178:179], v[20:21], off offset:-32
	global_load_dwordx2 v[176:177], v[20:21], off
	global_load_dwordx2 v[174:175], v[20:21], off offset:32
	v_lshl_add_u64 v[20:21], s[66:67], 0, v[156:157]
	global_load_dwordx2 v[172:173], v[20:21], off offset:-64
	global_load_dwordx2 v[170:171], v[20:21], off offset:-32
	global_load_dwordx2 v[168:169], v[20:21], off
	global_load_dwordx2 v[166:167], v[20:21], off offset:32
	v_lshl_add_u64 v[0:1], s[66:67], 0, v[142:143]
	global_load_dwordx4 v[12:15], v[0:1], off
	v_lshl_add_u64 v[0:1], s[66:67], 0, v[144:145]
	global_load_dwordx4 v[8:11], v[0:1], off
	v_lshl_add_u64 v[0:1], s[66:67], 0, v[146:147]
	global_load_dwordx4 v[4:7], v[0:1], off
	v_lshl_add_u64 v[0:1], s[66:67], 0, v[148:149]
	global_load_dwordx4 v[0:3], v[0:1], off
	v_cndmask_b32_e64 v20, 0, 1, s[54:55]
	v_cmp_ne_u32_e64 s[40:41], 1, v20
	s_andn2_b64 vcc, exec, s[54:55]
	s_waitcnt lgkmcnt(0)
	s_barrier
	s_cbranch_vccnz .LBB0_222
	ds_read_b64_tr_b16 v[28:29], v185
	ds_read_b64_tr_b16 v[30:31], v186
	ds_read_b64_tr_b16 v[24:25], v187
	ds_read_b64_tr_b16 v[26:27], v188
	ds_read_b64_tr_b16 v[20:21], v189
	ds_read_b64_tr_b16 v[22:23], v190
	ds_read_b64_tr_b16 v[234:235], v191
	ds_read_b64_tr_b16 v[236:237], v192
	s_waitcnt lgkmcnt(0)
	s_waitcnt vmcnt(19)
	v_mfma_f32_16x16x32_bf16 v[44:47], v[28:31], v[16:19], 0
	s_waitcnt vmcnt(18)
	v_mfma_f32_16x16x32_bf16 v[28:31], v[28:31], v[76:79], 0
	v_mfma_f32_16x16x32_bf16 v[40:43], v[24:27], v[16:19], 0
	v_mfma_f32_16x16x32_bf16 v[24:27], v[24:27], v[76:79], 0
	v_mfma_f32_16x16x32_bf16 v[36:39], v[20:23], v[16:19], 0
	v_mfma_f32_16x16x32_bf16 v[20:23], v[20:23], v[76:79], 0
	v_mfma_f32_16x16x32_bf16 v[32:35], v[234:237], v[16:19], 0
	v_mfma_f32_16x16x32_bf16 v[16:19], v[234:237], v[76:79], 0
	v_cndmask_b32_e64 v64, 0, 1, s[56:57]
	v_cmp_ne_u32_e64 s[42:43], 1, v64
	s_andn2_b64 vcc, exec, s[56:57]
	s_cbranch_vccz .LBB0_223
	s_branch .LBB0_224
; __device__ __forceinline__ void sgu_phase(const Ctx& C, const bf16_t* Z1, const float* VSS, const float* gv, const bf16_t* WSB, const float* bs, bf16_t* Gout) {
;     ...
;             for (int kk = 0; kk < 4; ++kk) {
;                 if (kk <= tb) {
;                     unsigned ad[8]; bf16x8 vf[4];
; #pragma unroll
;                     for (int nt = 0; nt < 4; ++nt) { ad[2 * nt] = ldsbase + tr_read_addr_16(lane, 4 * dh + nt, kk, 0); ad[2 * nt + 1] = ldsbase + tr_read_addr_16(lane, 4 * dh + nt, kk, 1); }
;                     tr_read8(vf, ad);
; #pragma unroll
;                     for (int nt = 0; nt < 4; ++nt)
; #pragma unroll
;                         for (int mt = 0; mt < 2; ++mt) acc[mt][nt] = __builtin_amdgcn_mfma_f32_16x16x32_bf16(vf[nt], wf[kk][mt], acc[mt][nt], 0, 0, 0);
;                 }
;             }
.LBB0_222:
	v_mov_b32_e32 v64, v65
	v_mov_b32_e32 v66, v65
	v_mov_b32_e32 v67, v65
	s_waitcnt vmcnt(19)
	v_mov_b64_e32 v[16:17], v[64:65]
	v_mov_b64_e32 v[20:21], v[64:65]
	v_mov_b64_e32 v[24:25], v[64:65]
	v_mov_b64_e32 v[28:29], v[64:65]
	v_mov_b64_e32 v[32:33], v[64:65]
	v_mov_b64_e32 v[36:37], v[64:65]
	v_mov_b64_e32 v[40:41], v[64:65]
	v_mov_b64_e32 v[44:45], v[64:65]
	v_mov_b64_e32 v[18:19], v[66:67]
	v_mov_b64_e32 v[22:23], v[66:67]
	v_mov_b64_e32 v[26:27], v[66:67]
	v_mov_b64_e32 v[30:31], v[66:67]
	v_mov_b64_e32 v[34:35], v[66:67]
	v_mov_b64_e32 v[38:39], v[66:67]
	v_mov_b64_e32 v[42:43], v[66:67]
	v_mov_b64_e32 v[46:47], v[66:67]
	v_cndmask_b32_e64 v64, 0, 1, s[56:57]
	v_cmp_ne_u32_e64 s[42:43], 1, v64
	s_andn2_b64 vcc, exec, s[56:57]
	s_cbranch_vccnz .LBB0_224
.LBB0_223:
	s_waitcnt vmcnt(18)
	ds_read_b64_tr_b16 v[194:195], v193
	ds_read_b64_tr_b16 v[196:197], v206
	ds_read_b64_tr_b16 v[244:245], v207
	ds_read_b64_tr_b16 v[246:247], v208
	ds_read_b64_tr_b16 v[234:235], v209
	ds_read_b64_tr_b16 v[236:237], v210
	ds_read_b64_tr_b16 v[76:77], v211
	ds_read_b64_tr_b16 v[78:79], v212
	s_waitcnt lgkmcnt(0)
	s_waitcnt vmcnt(17)
	v_mfma_f32_16x16x32_bf16 v[44:47], v[194:197], v[68:71], v[44:47]
	s_waitcnt vmcnt(16)
	v_mfma_f32_16x16x32_bf16 v[28:31], v[194:197], v[72:75], v[28:31]
	v_mfma_f32_16x16x32_bf16 v[40:43], v[244:247], v[68:71], v[40:43]
	v_mfma_f32_16x16x32_bf16 v[24:27], v[244:247], v[72:75], v[24:27]
	v_mfma_f32_16x16x32_bf16 v[36:39], v[234:237], v[68:71], v[36:39]
	v_mfma_f32_16x16x32_bf16 v[20:23], v[234:237], v[72:75], v[20:23]
	v_mfma_f32_16x16x32_bf16 v[32:35], v[76:79], v[68:71], v[32:35]
	v_mfma_f32_16x16x32_bf16 v[16:19], v[76:79], v[72:75], v[16:19]
.LBB0_224:
	v_cndmask_b32_e64 v64, 0, 1, s[58:59]
	v_cmp_ne_u32_e64 s[44:45], 1, v64
	s_andn2_b64 vcc, exec, s[58:59]
	s_cbranch_vccnz .LBB0_226
	s_waitcnt vmcnt(16)
	ds_read_b64_tr_b16 v[194:195], v213
	ds_read_b64_tr_b16 v[196:197], v214
	ds_read_b64_tr_b16 v[74:75], v215
	ds_read_b64_tr_b16 v[76:77], v216
	ds_read_b64_tr_b16 v[70:71], v217
	ds_read_b64_tr_b16 v[72:73], v218
	ds_read_b64_tr_b16 v[66:67], v219
	ds_read_b64_tr_b16 v[68:69], v220
	s_waitcnt lgkmcnt(0)
	s_waitcnt vmcnt(15)
	v_mfma_f32_16x16x32_bf16 v[44:47], v[194:197], v[56:59], v[44:47]
	s_waitcnt vmcnt(14)
	v_mfma_f32_16x16x32_bf16 v[28:31], v[194:197], v[60:63], v[28:31]
	v_mfma_f32_16x16x32_bf16 v[40:43], v[74:77], v[56:59], v[40:43]
	v_mfma_f32_16x16x32_bf16 v[24:27], v[74:77], v[60:63], v[24:27]
	v_mfma_f32_16x16x32_bf16 v[36:39], v[70:73], v[56:59], v[36:39]
	v_mfma_f32_16x16x32_bf16 v[20:23], v[70:73], v[60:63], v[20:23]
	v_mfma_f32_16x16x32_bf16 v[32:35], v[66:69], v[56:59], v[32:35]
	v_mfma_f32_16x16x32_bf16 v[16:19], v[66:69], v[60:63], v[16:19]
	v_cndmask_b32_e64 v56, 0, 1, s[70:71]
	v_cmp_ne_u32_e64 s[46:47], 1, v56
	s_andn2_b64 vcc, exec, s[70:71]
	s_cbranch_vccnz .LBB0_219
	s_branch .LBB0_227
.LBB0_226:
	s_waitcnt vmcnt(15)
	v_cndmask_b32_e64 v56, 0, 1, s[70:71]
	v_cmp_ne_u32_e64 s[46:47], 1, v56
	s_andn2_b64 vcc, exec, s[70:71]
	s_cbranch_vccnz .LBB0_219
.LBB0_227:
	s_waitcnt vmcnt(14)
	ds_read_b64_tr_b16 v[70:71], v221
	ds_read_b64_tr_b16 v[72:73], v222
	ds_read_b64_tr_b16 v[66:67], v223
	ds_read_b64_tr_b16 v[68:69], v224
	ds_read_b64_tr_b16 v[60:61], v225
	ds_read_b64_tr_b16 v[62:63], v226
	ds_read_b64_tr_b16 v[56:57], v227
	ds_read_b64_tr_b16 v[58:59], v228
	s_waitcnt lgkmcnt(0)
	s_waitcnt vmcnt(13)
	v_mfma_f32_16x16x32_bf16 v[44:47], v[70:73], v[48:51], v[44:47]
	s_waitcnt vmcnt(12)
	v_mfma_f32_16x16x32_bf16 v[28:31], v[70:73], v[52:55], v[28:31]
	v_mfma_f32_16x16x32_bf16 v[40:43], v[66:69], v[48:51], v[40:43]
	v_mfma_f32_16x16x32_bf16 v[24:27], v[66:69], v[52:55], v[24:27]
	v_mfma_f32_16x16x32_bf16 v[36:39], v[60:63], v[48:51], v[36:39]
	v_mfma_f32_16x16x32_bf16 v[20:23], v[60:63], v[52:55], v[20:23]
	v_mfma_f32_16x16x32_bf16 v[32:35], v[56:59], v[48:51], v[32:35]
	v_mfma_f32_16x16x32_bf16 v[16:19], v[56:59], v[52:55], v[16:19]
	s_branch .LBB0_219
